# gate/up epilogue: row scale folded into the sigmoid denominator (3 mul + 1 fma per output instead of 5 mul + add), still f32
# speedup vs baseline: 1.0116x; 1.0105x over previous
.LBB0_788:
	s_waitcnt lgkmcnt(0)
	v_mul_f32_e32 v246, 0xbfb8aa3b, v16
	v_mul_f32_e32 v247, v16, v16
	v_rcp_f32_e32 v247, v247
	v_mul_f32_e32 v8, v8, v12
	v_mul_f32_e32 v9, v9, v13
	v_mul_f32_e32 v10, v10, v14
	v_mul_f32_e32 v11, v11, v15
	v_mul_f32_e32 v0, v0, v4
	v_mul_f32_e32 v1, v1, v5
	v_mul_f32_e32 v2, v2, v6
	v_mul_f32_e32 v3, v3, v7
	v_mul_f32_e32 v12, v246, v12
	v_mul_f32_e32 v13, v246, v13
	v_mul_f32_e32 v14, v246, v14
	v_mul_f32_e32 v15, v246, v15
	v_mul_f32_e32 v4, v246, v4
	v_mul_f32_e32 v5, v246, v5
	v_mul_f32_e32 v6, v246, v6
	v_mul_f32_e32 v7, v246, v7
	v_exp_f32_e32 v12, v12
	v_exp_f32_e32 v13, v13
	v_exp_f32_e32 v14, v14
	v_exp_f32_e32 v15, v15
	v_exp_f32_e32 v4, v4
	v_exp_f32_e32 v5, v5
	v_exp_f32_e32 v6, v6
	v_exp_f32_e32 v7, v7
	v_fma_f32 v12, v12, v247, v247
	v_fma_f32 v13, v13, v247, v247
	v_fma_f32 v14, v14, v247, v247
	v_fma_f32 v15, v15, v247, v247
	v_fma_f32 v4, v4, v247, v247
	v_fma_f32 v5, v5, v247, v247
	v_fma_f32 v6, v6, v247, v247
	v_fma_f32 v7, v7, v247, v247
	v_rcp_f32_e32 v12, v12
	v_rcp_f32_e32 v13, v13
	v_rcp_f32_e32 v14, v14
	v_rcp_f32_e32 v15, v15
	v_rcp_f32_e32 v4, v4
	v_rcp_f32_e32 v5, v5
	v_rcp_f32_e32 v6, v6
	v_rcp_f32_e32 v7, v7
	v_mul_f32_e32 v8, v8, v12
	v_mul_f32_e32 v9, v9, v13
	v_mul_f32_e32 v10, v10, v14
	v_mul_f32_e32 v11, v11, v15
	v_mul_f32_e32 v0, v0, v4
	v_mul_f32_e32 v1, v1, v5
	v_mul_f32_e32 v2, v2, v6
	v_mul_f32_e32 v3, v3, v7
	v_cvt_pk_bf16_f32 v12, v8, v9
	v_cvt_pk_bf16_f32 v13, v10, v11
	v_cvt_pk_bf16_f32 v14, v0, v1
	v_cvt_pk_bf16_f32 v15, v2, v3
	s_and_b64 vcc, exec, s[6:7]
	s_mov_b32 s8, s18
	s_mov_b32 s28, s20
	s_mov_b64 s[62:63], s[24:25]
	s_mov_b64 s[58:59], s[22:23]
	v_add_u32_e32 v4, v17, v139
	v_mov_b32_e32 v5, 0x16000
	v_lshl_add_u32 v4, v4, 1, v5
	buffer_store_dwordx4 v[12:15], v4, s[36:39], 0 offen sc1
	s_cbranch_vccnz .LBB0_825

.LBB0_797:
	s_waitcnt lgkmcnt(0)
	v_mul_f32_e32 v246, 0xbfb8aa3b, v140
	v_mul_f32_e32 v247, v140, v140
	v_rcp_f32_e32 v247, v247
	v_mul_f32_e32 v120, v120, v124
	v_mul_f32_e32 v121, v121, v125
	v_mul_f32_e32 v122, v122, v126
	v_mul_f32_e32 v123, v123, v127
	v_mul_f32_e32 v112, v112, v116
	v_mul_f32_e32 v113, v113, v117
	v_mul_f32_e32 v114, v114, v118
	v_mul_f32_e32 v115, v115, v119
	v_mul_f32_e32 v124, v246, v124
	v_mul_f32_e32 v125, v246, v125
	v_mul_f32_e32 v126, v246, v126
	v_mul_f32_e32 v127, v246, v127
	v_mul_f32_e32 v116, v246, v116
	v_mul_f32_e32 v117, v246, v117
	v_mul_f32_e32 v118, v246, v118
	v_mul_f32_e32 v119, v246, v119
	v_exp_f32_e32 v124, v124
	v_exp_f32_e32 v125, v125
	v_exp_f32_e32 v126, v126
	v_exp_f32_e32 v127, v127
	v_exp_f32_e32 v116, v116
	v_exp_f32_e32 v117, v117
	v_exp_f32_e32 v118, v118
	v_exp_f32_e32 v119, v119
	v_fma_f32 v124, v124, v247, v247
	v_fma_f32 v125, v125, v247, v247
	v_fma_f32 v126, v126, v247, v247
	v_fma_f32 v127, v127, v247, v247
	v_fma_f32 v116, v116, v247, v247
	v_fma_f32 v117, v117, v247, v247
	v_fma_f32 v118, v118, v247, v247
	v_fma_f32 v119, v119, v247, v247
	v_rcp_f32_e32 v124, v124
	v_rcp_f32_e32 v125, v125
	v_rcp_f32_e32 v126, v126
	v_rcp_f32_e32 v127, v127
	v_rcp_f32_e32 v116, v116
	v_rcp_f32_e32 v117, v117
	v_rcp_f32_e32 v118, v118
	v_rcp_f32_e32 v119, v119
	v_mul_f32_e32 v120, v120, v124
	v_mul_f32_e32 v121, v121, v125
	v_mul_f32_e32 v122, v122, v126
	v_mul_f32_e32 v123, v123, v127
	v_mul_f32_e32 v112, v112, v116
	v_mul_f32_e32 v113, v113, v117
	v_mul_f32_e32 v114, v114, v118
	v_mul_f32_e32 v115, v115, v119
	v_cvt_pk_bf16_f32 v124, v120, v121
	v_cvt_pk_bf16_f32 v125, v122, v123
	v_cvt_pk_bf16_f32 v126, v112, v113
	v_cvt_pk_bf16_f32 v127, v114, v115
	s_movk_i32 s1, 0xb00
	v_lshl_or_b32 v139, s8, 7, v144
	s_mov_b64 s[58:59], -1
	s_andn2_b64 vcc, exec, s[28:29]
	v_mul_lo_u32 v113, v138, s1
	v_add_lshl_u32 v112, v113, v139, 1
	buffer_store_dwordx4 v[124:127], v112, s[36:39], 0 offen sc1
	v_cndmask_b32_e64 v112, 0, 1, s[28:29]
	v_cmp_ne_u32_e64 s[8:9], 1, v112
	v_or_b32_e32 v114, 16, v138
	s_cbranch_vccnz .LBB0_799
	v_ashrrev_i32_e32 v115, 31, v114
	v_lshlrev_b64 v[116:117], 6, v[114:115]
	v_lshl_add_u64 v[146:147], s[94:95], 0, v[116:117]
	global_load_dwordx4 v[116:119], v[146:147], off offset:48
	global_load_dwordx4 v[120:123], v[146:147], off offset:32
	global_load_dwordx4 v[124:127], v[146:147], off offset:16
	s_nop 0
	global_load_dwordx4 v[146:149], v[146:147], off
	s_mov_b64 s[58:59], 0
	s_waitcnt vmcnt(0)
	v_add_f32_e32 v120, v120, v121
	v_add_f32_e32 v122, v122, v123
	v_mov_b32_e32 v150, v147
	v_mov_b32_e32 v151, v148
	v_mov_b32_e32 v147, v149
	v_mov_b32_e32 v148, v125
	v_mov_b32_e32 v149, v126
	v_mov_b32_e32 v125, v127
	v_pk_add_f32 v[146:147], v[150:151], v[146:147]
	v_pk_add_f32 v[124:125], v[148:149], v[124:125]
	v_pk_add_f32 v[146:147], v[146:147], v[146:147] op_sel:[0,1] op_sel_hi:[1,0]
	v_pk_add_f32 v[124:125], v[124:125], v[124:125] op_sel:[0,1] op_sel_hi:[1,0]
	v_mov_b32_e32 v147, v116
	v_mov_b32_e32 v125, v117
	v_mov_b32_e32 v121, v118
	v_mov_b32_e32 v123, v119
	v_pk_add_f32 v[116:117], v[146:147], v[124:125]
	v_pk_add_f32 v[118:119], v[120:121], v[122:123]
	s_nop 0
	v_pk_add_f32 v[116:117], v[116:117], v[118:119]
	s_nop 0
	v_add_f32_e32 v112, v116, v117
	v_fmamk_f32 v112, v112, 0x3a800000, v193
	v_cmp_gt_f32_e32 vcc, s40, v112
	v_mul_f32_e32 v115, 0x4b800000, v112
	s_nop 0
	v_cndmask_b32_e32 v112, v112, v115, vcc
	v_rsq_f32_e32 v112, v112
	s_nop 0
	v_mul_f32_e32 v115, 0x45800000, v112
	v_cndmask_b32_e32 v112, v112, v115, vcc

.LBB0_801:
	s_waitcnt lgkmcnt(0)
	v_mul_f32_e32 v246, 0xbfb8aa3b, v112
	v_mul_f32_e32 v247, v112, v112
	v_rcp_f32_e32 v247, v247
	v_mul_f32_e32 v104, v104, v108
	v_mul_f32_e32 v105, v105, v109
	v_mul_f32_e32 v106, v106, v110
	v_mul_f32_e32 v107, v107, v111
	v_mul_f32_e32 v96, v96, v100
	v_mul_f32_e32 v97, v97, v101
	v_mul_f32_e32 v98, v98, v102
	v_mul_f32_e32 v99, v99, v103
	v_mul_f32_e32 v108, v246, v108
	v_mul_f32_e32 v109, v246, v109
	v_mul_f32_e32 v110, v246, v110
	v_mul_f32_e32 v111, v246, v111
	v_mul_f32_e32 v100, v246, v100
	v_mul_f32_e32 v101, v246, v101
	v_mul_f32_e32 v102, v246, v102
	v_mul_f32_e32 v103, v246, v103
	v_exp_f32_e32 v108, v108
	v_exp_f32_e32 v109, v109
	v_exp_f32_e32 v110, v110
	v_exp_f32_e32 v111, v111
	v_exp_f32_e32 v100, v100
	v_exp_f32_e32 v101, v101
	v_exp_f32_e32 v102, v102
	v_exp_f32_e32 v103, v103
	v_fma_f32 v108, v108, v247, v247
	v_fma_f32 v109, v109, v247, v247
	v_fma_f32 v110, v110, v247, v247
	v_fma_f32 v111, v111, v247, v247
	v_fma_f32 v100, v100, v247, v247
	v_fma_f32 v101, v101, v247, v247
	v_fma_f32 v102, v102, v247, v247
	v_fma_f32 v103, v103, v247, v247
	v_rcp_f32_e32 v108, v108
	v_rcp_f32_e32 v109, v109
	v_rcp_f32_e32 v110, v110
	v_rcp_f32_e32 v111, v111
	v_rcp_f32_e32 v100, v100
	v_rcp_f32_e32 v101, v101
	v_rcp_f32_e32 v102, v102
	v_rcp_f32_e32 v103, v103
	v_mul_f32_e32 v104, v104, v108
	v_mul_f32_e32 v105, v105, v109
	v_mul_f32_e32 v106, v106, v110
	v_mul_f32_e32 v107, v107, v111
	v_mul_f32_e32 v96, v96, v100
	v_mul_f32_e32 v97, v97, v101
	v_mul_f32_e32 v98, v98, v102
	v_mul_f32_e32 v99, v99, v103
	v_cvt_pk_bf16_f32 v108, v104, v105
	v_cvt_pk_bf16_f32 v109, v106, v107
	v_cvt_pk_bf16_f32 v110, v96, v97
	v_cvt_pk_bf16_f32 v111, v98, v99
	s_mov_b64 s[28:29], -1
	s_and_b64 vcc, exec, s[8:9]
	v_add_u32_e32 v97, 0xb000, v113
	v_add_lshl_u32 v96, v97, v139, 1
	buffer_store_dwordx4 v[108:111], v96, s[36:39], 0 offen sc1
	s_nop 1
	v_or_b32_e32 v98, 32, v138
	s_cbranch_vccnz .LBB0_803
	v_ashrrev_i32_e32 v99, 31, v98
	v_lshlrev_b64 v[100:101], 6, v[98:99]
	v_lshl_add_u64 v[112:113], s[94:95], 0, v[100:101]
	global_load_dwordx4 v[100:103], v[112:113], off offset:48
	global_load_dwordx4 v[104:107], v[112:113], off offset:32
	global_load_dwordx4 v[108:111], v[112:113], off offset:16
	s_nop 0
	global_load_dwordx4 v[112:115], v[112:113], off
	s_mov_b64 s[28:29], 0
	s_waitcnt vmcnt(0)
	v_add_f32_e32 v104, v104, v105
	v_add_f32_e32 v106, v106, v107
	v_mov_b32_e32 v116, v113
	v_mov_b32_e32 v117, v114
	v_mov_b32_e32 v113, v115
	v_mov_b32_e32 v114, v109
	v_mov_b32_e32 v115, v110
	v_mov_b32_e32 v109, v111
	v_pk_add_f32 v[112:113], v[116:117], v[112:113]
	v_pk_add_f32 v[108:109], v[114:115], v[108:109]
	v_pk_add_f32 v[112:113], v[112:113], v[112:113] op_sel:[0,1] op_sel_hi:[1,0]
	v_pk_add_f32 v[108:109], v[108:109], v[108:109] op_sel:[0,1] op_sel_hi:[1,0]
	v_mov_b32_e32 v113, v100
	v_mov_b32_e32 v109, v101
	v_mov_b32_e32 v105, v102
	v_mov_b32_e32 v107, v103
	v_pk_add_f32 v[100:101], v[112:113], v[108:109]
	v_pk_add_f32 v[102:103], v[104:105], v[106:107]
	s_nop 0
	v_pk_add_f32 v[100:101], v[100:101], v[102:103]
	s_nop 0
	v_add_f32_e32 v96, v100, v101
	v_fmamk_f32 v96, v96, 0x3a800000, v193
	v_cmp_gt_f32_e32 vcc, s40, v96
	v_mul_f32_e32 v99, 0x4b800000, v96
	s_nop 0
	v_cndmask_b32_e32 v96, v96, v99, vcc
	v_rsq_f32_e32 v96, v96
	s_nop 0
	v_mul_f32_e32 v99, 0x45800000, v96
	v_cndmask_b32_e32 v96, v96, v99, vcc

.LBB0_805:
	s_waitcnt lgkmcnt(0)
	v_mul_f32_e32 v246, 0xbfb8aa3b, v96
	v_mul_f32_e32 v247, v96, v96
	v_rcp_f32_e32 v247, v247
	v_mul_f32_e32 v88, v88, v92
	v_mul_f32_e32 v89, v89, v93
	v_mul_f32_e32 v90, v90, v94
	v_mul_f32_e32 v91, v91, v95
	v_mul_f32_e32 v80, v80, v84
	v_mul_f32_e32 v81, v81, v85
	v_mul_f32_e32 v82, v82, v86
	v_mul_f32_e32 v83, v83, v87
	v_mul_f32_e32 v92, v246, v92
	v_mul_f32_e32 v93, v246, v93
	v_mul_f32_e32 v94, v246, v94
	v_mul_f32_e32 v95, v246, v95
	v_mul_f32_e32 v84, v246, v84
	v_mul_f32_e32 v85, v246, v85
	v_mul_f32_e32 v86, v246, v86
	v_mul_f32_e32 v87, v246, v87
	v_exp_f32_e32 v92, v92
	v_exp_f32_e32 v93, v93
	v_exp_f32_e32 v94, v94
	v_exp_f32_e32 v95, v95
	v_exp_f32_e32 v84, v84
	v_exp_f32_e32 v85, v85
	v_exp_f32_e32 v86, v86
	v_exp_f32_e32 v87, v87
	v_fma_f32 v92, v92, v247, v247
	v_fma_f32 v93, v93, v247, v247
	v_fma_f32 v94, v94, v247, v247
	v_fma_f32 v95, v95, v247, v247
	v_fma_f32 v84, v84, v247, v247
	v_fma_f32 v85, v85, v247, v247
	v_fma_f32 v86, v86, v247, v247
	v_fma_f32 v87, v87, v247, v247
	v_rcp_f32_e32 v92, v92
	v_rcp_f32_e32 v93, v93
	v_rcp_f32_e32 v94, v94
	v_rcp_f32_e32 v95, v95
	v_rcp_f32_e32 v84, v84
	v_rcp_f32_e32 v85, v85
	v_rcp_f32_e32 v86, v86
	v_rcp_f32_e32 v87, v87
	v_mul_f32_e32 v88, v88, v92
	v_mul_f32_e32 v89, v89, v93
	v_mul_f32_e32 v90, v90, v94
	v_mul_f32_e32 v91, v91, v95
	v_mul_f32_e32 v80, v80, v84
	v_mul_f32_e32 v81, v81, v85
	v_mul_f32_e32 v82, v82, v86
	v_mul_f32_e32 v83, v83, v87
	v_cvt_pk_bf16_f32 v92, v88, v89
	v_cvt_pk_bf16_f32 v93, v90, v91
	v_cvt_pk_bf16_f32 v94, v80, v81
	v_cvt_pk_bf16_f32 v95, v82, v83
	s_mov_b64 s[28:29], -1
	s_and_b64 vcc, exec, s[8:9]
	v_add_u32_e32 v81, 0xb000, v97
	v_add_lshl_u32 v80, v81, v139, 1
	buffer_store_dwordx4 v[92:95], v80, s[36:39], 0 offen sc1
	s_nop 1
	v_or_b32_e32 v82, 48, v138
	s_cbranch_vccnz .LBB0_807
	v_ashrrev_i32_e32 v83, 31, v82
	v_lshlrev_b64 v[84:85], 6, v[82:83]
	v_lshl_add_u64 v[96:97], s[94:95], 0, v[84:85]
	global_load_dwordx4 v[84:87], v[96:97], off offset:48
	global_load_dwordx4 v[88:91], v[96:97], off offset:32
	global_load_dwordx4 v[92:95], v[96:97], off offset:16
	s_nop 0
	global_load_dwordx4 v[96:99], v[96:97], off
	s_mov_b64 s[28:29], 0
	s_waitcnt vmcnt(0)
	v_add_f32_e32 v88, v88, v89
	v_add_f32_e32 v90, v90, v91
	v_mov_b32_e32 v100, v97
	v_mov_b32_e32 v101, v98
	v_mov_b32_e32 v97, v99
	v_mov_b32_e32 v98, v93
	v_mov_b32_e32 v99, v94
	v_mov_b32_e32 v93, v95
	v_pk_add_f32 v[96:97], v[100:101], v[96:97]
	v_pk_add_f32 v[92:93], v[98:99], v[92:93]
	v_pk_add_f32 v[96:97], v[96:97], v[96:97] op_sel:[0,1] op_sel_hi:[1,0]
	v_pk_add_f32 v[92:93], v[92:93], v[92:93] op_sel:[0,1] op_sel_hi:[1,0]
	v_mov_b32_e32 v97, v84
	v_mov_b32_e32 v93, v85
	v_mov_b32_e32 v89, v86
	v_mov_b32_e32 v91, v87
	v_pk_add_f32 v[84:85], v[96:97], v[92:93]
	v_pk_add_f32 v[86:87], v[88:89], v[90:91]
	s_nop 0
	v_pk_add_f32 v[84:85], v[84:85], v[86:87]
	s_nop 0
	v_add_f32_e32 v80, v84, v85
	v_fmamk_f32 v80, v80, 0x3a800000, v193
	v_cmp_gt_f32_e32 vcc, s40, v80
	v_mul_f32_e32 v83, 0x4b800000, v80
	s_nop 0
	v_cndmask_b32_e32 v80, v80, v83, vcc
	v_rsq_f32_e32 v80, v80
	s_nop 0
	v_mul_f32_e32 v83, 0x45800000, v80
	v_cndmask_b32_e32 v80, v80, v83, vcc

.LBB0_809:
	s_waitcnt lgkmcnt(0)
	v_mul_f32_e32 v246, 0xbfb8aa3b, v80
	v_mul_f32_e32 v247, v80, v80
	v_rcp_f32_e32 v247, v247
	v_mul_f32_e32 v72, v72, v76
	v_mul_f32_e32 v73, v73, v77
	v_mul_f32_e32 v74, v74, v78
	v_mul_f32_e32 v75, v75, v79
	v_mul_f32_e32 v64, v64, v68
	v_mul_f32_e32 v65, v65, v69
	v_mul_f32_e32 v66, v66, v70
	v_mul_f32_e32 v67, v67, v71
	v_mul_f32_e32 v76, v246, v76
	v_mul_f32_e32 v77, v246, v77
	v_mul_f32_e32 v78, v246, v78
	v_mul_f32_e32 v79, v246, v79
	v_mul_f32_e32 v68, v246, v68
	v_mul_f32_e32 v69, v246, v69
	v_mul_f32_e32 v70, v246, v70
	v_mul_f32_e32 v71, v246, v71
	v_exp_f32_e32 v76, v76
	v_exp_f32_e32 v77, v77
	v_exp_f32_e32 v78, v78
	v_exp_f32_e32 v79, v79
	v_exp_f32_e32 v68, v68
	v_exp_f32_e32 v69, v69
	v_exp_f32_e32 v70, v70
	v_exp_f32_e32 v71, v71
	v_fma_f32 v76, v76, v247, v247
	v_fma_f32 v77, v77, v247, v247
	v_fma_f32 v78, v78, v247, v247
	v_fma_f32 v79, v79, v247, v247
	v_fma_f32 v68, v68, v247, v247
	v_fma_f32 v69, v69, v247, v247
	v_fma_f32 v70, v70, v247, v247
	v_fma_f32 v71, v71, v247, v247
	v_rcp_f32_e32 v76, v76
	v_rcp_f32_e32 v77, v77
	v_rcp_f32_e32 v78, v78
	v_rcp_f32_e32 v79, v79
	v_rcp_f32_e32 v68, v68
	v_rcp_f32_e32 v69, v69
	v_rcp_f32_e32 v70, v70
	v_rcp_f32_e32 v71, v71
	v_mul_f32_e32 v72, v72, v76
	v_mul_f32_e32 v73, v73, v77
	v_mul_f32_e32 v74, v74, v78
	v_mul_f32_e32 v75, v75, v79
	v_mul_f32_e32 v64, v64, v68
	v_mul_f32_e32 v65, v65, v69
	v_mul_f32_e32 v66, v66, v70
	v_mul_f32_e32 v67, v67, v71
	v_cvt_pk_bf16_f32 v76, v72, v73
	v_cvt_pk_bf16_f32 v77, v74, v75
	v_cvt_pk_bf16_f32 v78, v64, v65
	v_cvt_pk_bf16_f32 v79, v66, v67
	s_mov_b64 s[28:29], -1
	s_and_b64 vcc, exec, s[8:9]
	v_add_u32_e32 v65, 0xb000, v81
	v_add_lshl_u32 v64, v65, v139, 1
	buffer_store_dwordx4 v[76:79], v64, s[36:39], 0 offen sc1
	s_nop 1
	v_add_u32_e32 v66, 0x80, v138
	s_cbranch_vccnz .LBB0_811
	v_ashrrev_i32_e32 v67, 31, v66
	v_lshlrev_b64 v[68:69], 6, v[66:67]
	v_lshl_add_u64 v[80:81], s[94:95], 0, v[68:69]
	global_load_dwordx4 v[68:71], v[80:81], off offset:48
	global_load_dwordx4 v[72:75], v[80:81], off offset:32
	global_load_dwordx4 v[76:79], v[80:81], off offset:16
	s_nop 0
	global_load_dwordx4 v[80:83], v[80:81], off
	s_mov_b64 s[28:29], 0
	s_waitcnt vmcnt(0)
	v_add_f32_e32 v72, v72, v73
	v_add_f32_e32 v74, v74, v75
	v_mov_b32_e32 v84, v81
	v_mov_b32_e32 v85, v82
	v_mov_b32_e32 v81, v83
	v_mov_b32_e32 v82, v77
	v_mov_b32_e32 v83, v78
	v_mov_b32_e32 v77, v79
	v_pk_add_f32 v[80:81], v[84:85], v[80:81]
	v_pk_add_f32 v[76:77], v[82:83], v[76:77]
	v_pk_add_f32 v[80:81], v[80:81], v[80:81] op_sel:[0,1] op_sel_hi:[1,0]
	v_pk_add_f32 v[76:77], v[76:77], v[76:77] op_sel:[0,1] op_sel_hi:[1,0]
	v_mov_b32_e32 v81, v68
	v_mov_b32_e32 v77, v69
	v_mov_b32_e32 v73, v70
	v_mov_b32_e32 v75, v71
	v_pk_add_f32 v[68:69], v[80:81], v[76:77]
	v_pk_add_f32 v[70:71], v[72:73], v[74:75]
	s_nop 0
	v_pk_add_f32 v[68:69], v[68:69], v[70:71]
	s_nop 0
	v_add_f32_e32 v64, v68, v69
	v_fmamk_f32 v64, v64, 0x3a800000, v193
	v_cmp_gt_f32_e32 vcc, s40, v64
	v_mul_f32_e32 v67, 0x4b800000, v64
	s_nop 0
	v_cndmask_b32_e32 v64, v64, v67, vcc
	v_rsq_f32_e32 v64, v64
	s_nop 0
	v_mul_f32_e32 v67, 0x45800000, v64
	v_cndmask_b32_e32 v64, v64, v67, vcc

.LBB0_813:
	s_waitcnt lgkmcnt(0)
	v_mul_f32_e32 v246, 0xbfb8aa3b, v64
	v_mul_f32_e32 v247, v64, v64
	v_rcp_f32_e32 v247, v247
	v_mul_f32_e32 v56, v56, v60
	v_mul_f32_e32 v57, v57, v61
	v_mul_f32_e32 v58, v58, v62
	v_mul_f32_e32 v59, v59, v63
	v_mul_f32_e32 v48, v48, v52
	v_mul_f32_e32 v49, v49, v53
	v_mul_f32_e32 v50, v50, v54
	v_mul_f32_e32 v51, v51, v55
	v_mul_f32_e32 v60, v246, v60
	v_mul_f32_e32 v61, v246, v61
	v_mul_f32_e32 v62, v246, v62
	v_mul_f32_e32 v63, v246, v63
	v_mul_f32_e32 v52, v246, v52
	v_mul_f32_e32 v53, v246, v53
	v_mul_f32_e32 v54, v246, v54
	v_mul_f32_e32 v55, v246, v55
	v_exp_f32_e32 v60, v60
	v_exp_f32_e32 v61, v61
	v_exp_f32_e32 v62, v62
	v_exp_f32_e32 v63, v63
	v_exp_f32_e32 v52, v52
	v_exp_f32_e32 v53, v53
	v_exp_f32_e32 v54, v54
	v_exp_f32_e32 v55, v55
	v_fma_f32 v60, v60, v247, v247
	v_fma_f32 v61, v61, v247, v247
	v_fma_f32 v62, v62, v247, v247
	v_fma_f32 v63, v63, v247, v247
	v_fma_f32 v52, v52, v247, v247
	v_fma_f32 v53, v53, v247, v247
	v_fma_f32 v54, v54, v247, v247
	v_fma_f32 v55, v55, v247, v247
	v_rcp_f32_e32 v60, v60
	v_rcp_f32_e32 v61, v61
	v_rcp_f32_e32 v62, v62
	v_rcp_f32_e32 v63, v63
	v_rcp_f32_e32 v52, v52
	v_rcp_f32_e32 v53, v53
	v_rcp_f32_e32 v54, v54
	v_rcp_f32_e32 v55, v55
	v_mul_f32_e32 v56, v56, v60
	v_mul_f32_e32 v57, v57, v61
	v_mul_f32_e32 v58, v58, v62
	v_mul_f32_e32 v59, v59, v63
	v_mul_f32_e32 v48, v48, v52
	v_mul_f32_e32 v49, v49, v53
	v_mul_f32_e32 v50, v50, v54
	v_mul_f32_e32 v51, v51, v55
	v_cvt_pk_bf16_f32 v60, v56, v57
	v_cvt_pk_bf16_f32 v61, v58, v59
	v_cvt_pk_bf16_f32 v62, v48, v49
	v_cvt_pk_bf16_f32 v63, v50, v51
	s_mov_b64 s[28:29], -1
	s_and_b64 vcc, exec, s[8:9]
	v_add_u32_e32 v49, 0x37000, v65
	v_add_lshl_u32 v48, v49, v139, 1
	buffer_store_dwordx4 v[60:63], v48, s[36:39], 0 offen sc1
	s_nop 1
	v_add_u32_e32 v50, 0x90, v138
	s_cbranch_vccnz .LBB0_815
	v_ashrrev_i32_e32 v51, 31, v50
	v_lshlrev_b64 v[52:53], 6, v[50:51]
	v_lshl_add_u64 v[64:65], s[94:95], 0, v[52:53]
	global_load_dwordx4 v[52:55], v[64:65], off offset:48
	global_load_dwordx4 v[56:59], v[64:65], off offset:32
	global_load_dwordx4 v[60:63], v[64:65], off offset:16
	s_nop 0
	global_load_dwordx4 v[64:67], v[64:65], off
	s_mov_b64 s[28:29], 0
	s_waitcnt vmcnt(0)
	v_add_f32_e32 v56, v56, v57
	v_add_f32_e32 v58, v58, v59
	v_mov_b32_e32 v68, v65
	v_mov_b32_e32 v69, v66
	v_mov_b32_e32 v65, v67
	v_mov_b32_e32 v66, v61
	v_mov_b32_e32 v67, v62
	v_mov_b32_e32 v61, v63
	v_pk_add_f32 v[64:65], v[68:69], v[64:65]
	v_pk_add_f32 v[60:61], v[66:67], v[60:61]
	v_pk_add_f32 v[64:65], v[64:65], v[64:65] op_sel:[0,1] op_sel_hi:[1,0]
	v_pk_add_f32 v[60:61], v[60:61], v[60:61] op_sel:[0,1] op_sel_hi:[1,0]
	v_mov_b32_e32 v65, v52
	v_mov_b32_e32 v61, v53
	v_mov_b32_e32 v57, v54
	v_mov_b32_e32 v59, v55
	v_pk_add_f32 v[52:53], v[64:65], v[60:61]
	v_pk_add_f32 v[54:55], v[56:57], v[58:59]
	s_nop 0
	v_pk_add_f32 v[52:53], v[52:53], v[54:55]
	s_nop 0
	v_add_f32_e32 v48, v52, v53
	v_fmamk_f32 v48, v48, 0x3a800000, v193
	v_cmp_gt_f32_e32 vcc, s40, v48
	v_mul_f32_e32 v51, 0x4b800000, v48
	s_nop 0
	v_cndmask_b32_e32 v48, v48, v51, vcc
	v_rsq_f32_e32 v48, v48
	s_nop 0
	v_mul_f32_e32 v51, 0x45800000, v48
	v_cndmask_b32_e32 v48, v48, v51, vcc

.LBB0_817:
	s_waitcnt lgkmcnt(0)
	v_mul_f32_e32 v246, 0xbfb8aa3b, v48
	v_mul_f32_e32 v247, v48, v48
	v_rcp_f32_e32 v247, v247
	v_mul_f32_e32 v40, v40, v44
	v_mul_f32_e32 v41, v41, v45
	v_mul_f32_e32 v42, v42, v46
	v_mul_f32_e32 v43, v43, v47
	v_mul_f32_e32 v32, v32, v36
	v_mul_f32_e32 v33, v33, v37
	v_mul_f32_e32 v34, v34, v38
	v_mul_f32_e32 v35, v35, v39
	v_mul_f32_e32 v44, v246, v44
	v_mul_f32_e32 v45, v246, v45
	v_mul_f32_e32 v46, v246, v46
	v_mul_f32_e32 v47, v246, v47
	v_mul_f32_e32 v36, v246, v36
	v_mul_f32_e32 v37, v246, v37
	v_mul_f32_e32 v38, v246, v38
	v_mul_f32_e32 v39, v246, v39
	v_exp_f32_e32 v44, v44
	v_exp_f32_e32 v45, v45
	v_exp_f32_e32 v46, v46
	v_exp_f32_e32 v47, v47
	v_exp_f32_e32 v36, v36
	v_exp_f32_e32 v37, v37
	v_exp_f32_e32 v38, v38
	v_exp_f32_e32 v39, v39
	v_fma_f32 v44, v44, v247, v247
	v_fma_f32 v45, v45, v247, v247
	v_fma_f32 v46, v46, v247, v247
	v_fma_f32 v47, v47, v247, v247
	v_fma_f32 v36, v36, v247, v247
	v_fma_f32 v37, v37, v247, v247
	v_fma_f32 v38, v38, v247, v247
	v_fma_f32 v39, v39, v247, v247
	v_rcp_f32_e32 v44, v44
	v_rcp_f32_e32 v45, v45
	v_rcp_f32_e32 v46, v46
	v_rcp_f32_e32 v47, v47
	v_rcp_f32_e32 v36, v36
	v_rcp_f32_e32 v37, v37
	v_rcp_f32_e32 v38, v38
	v_rcp_f32_e32 v39, v39
	v_mul_f32_e32 v40, v40, v44
	v_mul_f32_e32 v41, v41, v45
	v_mul_f32_e32 v42, v42, v46
	v_mul_f32_e32 v43, v43, v47
	v_mul_f32_e32 v32, v32, v36
	v_mul_f32_e32 v33, v33, v37
	v_mul_f32_e32 v34, v34, v38
	v_mul_f32_e32 v35, v35, v39
	v_cvt_pk_bf16_f32 v44, v40, v41
	v_cvt_pk_bf16_f32 v45, v42, v43
	v_cvt_pk_bf16_f32 v46, v32, v33
	v_cvt_pk_bf16_f32 v47, v34, v35
	s_mov_b64 s[28:29], -1
	s_and_b64 vcc, exec, s[8:9]
	v_add_u32_e32 v35, 0xb000, v49
	v_add_lshl_u32 v32, v35, v139, 1
	buffer_store_dwordx4 v[44:47], v32, s[36:39], 0 offen sc1
	v_add_u32_e32 v32, 0xa0, v138
	s_cbranch_vccnz .LBB0_819
	v_ashrrev_i32_e32 v33, 31, v32
	v_lshlrev_b64 v[36:37], 6, v[32:33]
	v_lshl_add_u64 v[48:49], s[94:95], 0, v[36:37]
	global_load_dwordx4 v[36:39], v[48:49], off offset:48
	global_load_dwordx4 v[40:43], v[48:49], off offset:32
	global_load_dwordx4 v[44:47], v[48:49], off offset:16
	s_nop 0
	global_load_dwordx4 v[48:51], v[48:49], off
	s_mov_b64 s[28:29], 0
	s_waitcnt vmcnt(0)
	v_add_f32_e32 v40, v40, v41
	v_add_f32_e32 v42, v42, v43
	v_mov_b32_e32 v52, v49
	v_mov_b32_e32 v53, v50
	v_mov_b32_e32 v49, v51
	v_mov_b32_e32 v50, v45
	v_mov_b32_e32 v51, v46
	v_mov_b32_e32 v45, v47
	v_pk_add_f32 v[48:49], v[52:53], v[48:49]
	v_pk_add_f32 v[44:45], v[50:51], v[44:45]
	v_pk_add_f32 v[48:49], v[48:49], v[48:49] op_sel:[0,1] op_sel_hi:[1,0]
	v_pk_add_f32 v[44:45], v[44:45], v[44:45] op_sel:[0,1] op_sel_hi:[1,0]
	v_mov_b32_e32 v49, v36
	v_mov_b32_e32 v45, v37
	v_mov_b32_e32 v41, v38
	v_mov_b32_e32 v43, v39
	v_pk_add_f32 v[36:37], v[48:49], v[44:45]
	v_pk_add_f32 v[38:39], v[40:41], v[42:43]
	s_nop 0
	v_pk_add_f32 v[36:37], v[36:37], v[38:39]
	s_nop 0
	v_add_f32_e32 v33, v36, v37
	v_fmamk_f32 v33, v33, 0x3a800000, v193
	v_cmp_gt_f32_e32 vcc, s40, v33
	v_mul_f32_e32 v34, 0x4b800000, v33
	s_nop 0
	v_cndmask_b32_e32 v33, v33, v34, vcc
	v_rsq_f32_e32 v33, v33
	s_nop 0
	v_mul_f32_e32 v34, 0x45800000, v33
	v_cndmask_b32_e32 v34, v33, v34, vcc

.LBB0_821:
	s_waitcnt lgkmcnt(0)
	v_mul_f32_e32 v246, 0xbfb8aa3b, v34
	v_mul_f32_e32 v247, v34, v34
	v_rcp_f32_e32 v247, v247
	v_mul_f32_e32 v24, v24, v28
	v_mul_f32_e32 v25, v25, v29
	v_mul_f32_e32 v26, v26, v30
	v_mul_f32_e32 v27, v27, v31
	v_mul_f32_e32 v16, v16, v20
	v_mul_f32_e32 v17, v17, v21
	v_mul_f32_e32 v18, v18, v22
	v_mul_f32_e32 v19, v19, v23
	v_mul_f32_e32 v28, v246, v28
	v_mul_f32_e32 v29, v246, v29
	v_mul_f32_e32 v30, v246, v30
	v_mul_f32_e32 v31, v246, v31
	v_mul_f32_e32 v20, v246, v20
	v_mul_f32_e32 v21, v246, v21
	v_mul_f32_e32 v22, v246, v22
	v_mul_f32_e32 v23, v246, v23
	v_exp_f32_e32 v28, v28
	v_exp_f32_e32 v29, v29
	v_exp_f32_e32 v30, v30
	v_exp_f32_e32 v31, v31
	v_exp_f32_e32 v20, v20
	v_exp_f32_e32 v21, v21
	v_exp_f32_e32 v22, v22
	v_exp_f32_e32 v23, v23
	v_fma_f32 v28, v28, v247, v247
	v_fma_f32 v29, v29, v247, v247
	v_fma_f32 v30, v30, v247, v247
	v_fma_f32 v31, v31, v247, v247
	v_fma_f32 v20, v20, v247, v247
	v_fma_f32 v21, v21, v247, v247
	v_fma_f32 v22, v22, v247, v247
	v_fma_f32 v23, v23, v247, v247
	v_rcp_f32_e32 v28, v28
	v_rcp_f32_e32 v29, v29
	v_rcp_f32_e32 v30, v30
	v_rcp_f32_e32 v31, v31
	v_rcp_f32_e32 v20, v20
	v_rcp_f32_e32 v21, v21
	v_rcp_f32_e32 v22, v22
	v_rcp_f32_e32 v23, v23
	v_mul_f32_e32 v24, v24, v28
	v_mul_f32_e32 v25, v25, v29
	v_mul_f32_e32 v26, v26, v30
	v_mul_f32_e32 v27, v27, v31
	v_mul_f32_e32 v16, v16, v20
	v_mul_f32_e32 v17, v17, v21
	v_mul_f32_e32 v18, v18, v22
	v_mul_f32_e32 v19, v19, v23
	v_cvt_pk_bf16_f32 v28, v24, v25
	v_cvt_pk_bf16_f32 v29, v26, v27
	v_cvt_pk_bf16_f32 v30, v16, v17
	v_cvt_pk_bf16_f32 v31, v18, v19
	s_and_b64 vcc, exec, s[8:9]
	s_mov_b64 s[8:9], -1
	v_add_u32_e32 v17, 0xb000, v35
	v_add_lshl_u32 v16, v17, v139, 1
	buffer_store_dwordx4 v[28:31], v16, s[36:39], 0 offen sc1
	s_nop 1
	v_add_u32_e32 v18, 0xb0, v138
	s_cbranch_vccnz .LBB0_823
	v_ashrrev_i32_e32 v19, 31, v18
	v_lshlrev_b64 v[20:21], 6, v[18:19]
	v_lshl_add_u64 v[32:33], s[94:95], 0, v[20:21]
	global_load_dwordx4 v[20:23], v[32:33], off offset:48
	global_load_dwordx4 v[24:27], v[32:33], off offset:32
	global_load_dwordx4 v[28:31], v[32:33], off offset:16
	s_nop 0
	global_load_dwordx4 v[32:35], v[32:33], off
	s_mov_b64 s[8:9], 0
	s_waitcnt vmcnt(0)
	v_add_f32_e32 v24, v24, v25
	v_add_f32_e32 v26, v26, v27
	v_mov_b32_e32 v36, v33
	v_mov_b32_e32 v37, v34
	v_mov_b32_e32 v33, v35
	v_mov_b32_e32 v34, v29
	v_mov_b32_e32 v35, v30
	v_mov_b32_e32 v29, v31
	v_pk_add_f32 v[32:33], v[36:37], v[32:33]
	v_pk_add_f32 v[28:29], v[34:35], v[28:29]
	v_pk_add_f32 v[32:33], v[32:33], v[32:33] op_sel:[0,1] op_sel_hi:[1,0]
	v_pk_add_f32 v[28:29], v[28:29], v[28:29] op_sel:[0,1] op_sel_hi:[1,0]
	v_mov_b32_e32 v33, v20
	v_mov_b32_e32 v29, v21
	v_mov_b32_e32 v25, v22
	v_mov_b32_e32 v27, v23
	v_pk_add_f32 v[20:21], v[32:33], v[28:29]
	v_pk_add_f32 v[22:23], v[24:25], v[26:27]
	s_nop 0
	v_pk_add_f32 v[20:21], v[20:21], v[22:23]
	s_nop 0
	v_add_f32_e32 v16, v20, v21
	v_fmamk_f32 v16, v16, 0x3a800000, v193
	v_cmp_gt_f32_e32 vcc, s40, v16
	v_mul_f32_e32 v19, 0x4b800000, v16
	s_nop 0
	v_cndmask_b32_e32 v16, v16, v19, vcc
	v_rsq_f32_e32 v16, v16
	s_nop 0
	v_mul_f32_e32 v19, 0x45800000, v16
	v_cndmask_b32_e32 v16, v16, v19, vcc
